# NA main tile loop: K/bias LDS reads in first-consumer order with counted lgkmcnt waits per consumer, V reads issued after block A exps (on pack_more)
# speedup vs baseline: 1.0043x; 1.0043x over previous
; #define LAS __attribute__((address_space(3)))
; __device__ __forceinline__ float vmax3(float a, float b, float c) { return __builtin_elementwise_maximum(__builtin_elementwise_maximum(a, b), c); }
; template <int MODE> ...
;     ...
;                     for (int ks = 0; ks < 2; ++ks) kf[jj][kt][ks] = *(const LAS bf16x8*)(Sl + kad[jj][ks] + (32 * hf + 16 * kt) * 128);
;             f32x4 bb[2][2];
; #pragma unroll
;             for (int jj = 0; jj < 2; ++jj) { const LAS f32x4* bl = bcp + ((MODE == 0) ? (dr0 + t - act0) * 8 : 16 * t + 8 * hf) + bofs[jj];
; #pragma unroll
;                 for (int kt = 0; kt < 2; ++kt) bb[jj][kt] = bl[4 * kt]; }
;             s16x4 vlo[2][4], vhi[2][4];
; #pragma unroll
;             for (int jj = 0; jj < 2; ++jj)
; #pragma unroll
;                 for (int dt = 0; dt < 4; ++dt) { const LAS unsigned char* vp = Sl + vad[jj] + (32 * hf) * 128 + ((dt ^ sv) << 5);
;                     vlo[jj][dt] = __builtin_bit_cast(s16x4, __builtin_amdgcn_ds_read_tr16_b64_v4i16((LAS s16x4*)(vp)));
;                     vhi[jj][dt] = __builtin_bit_cast(s16x4, __builtin_amdgcn_ds_read_tr16_b64_v4i16((LAS s16x4*)(vp + 2048))); }
;             __builtin_amdgcn_sched_barrier(0);
;             f32x4 s[2][2];
; #pragma unroll
;             for (int jj = 0; jj < 2; ++jj)
; #pragma unroll
;                 for (int kt = 0; kt < 2; ++kt) { f32x4 a = (MODE == 0) ? bb[jj][kt] + mneg[jj][kt] : bb[jj][kt];
;                     a = __builtin_amdgcn_mfma_f32_16x16x32_bf16(kf[jj][kt][0], qf[jj][0], a, 0, 0, 0);
;                     s[jj][kt] = __builtin_amdgcn_mfma_f32_16x16x32_bf16(kf[jj][kt][1], qf[jj][1], a, 0, 0, 0); }
;             u32x4 pw[2];
; #pragma unroll
;             for (int jj = 0; jj < 2; ++jj) {
;                 const float tm = vmax3(vmax3(s[jj][0][0], s[jj][0][1], s[jj][0][2]), vmax3(s[jj][0][3], s[jj][1][0], s[jj][1][1]), vmax3(s[jj][1][2], s[jj][1][3], s[jj][1][3]));
;                 const float mn = quad_max3(mrun[jj], tm);
;                 const float alpha = __builtin_amdgcn_exp2f(mrun[jj] - mn);
;                 mrun[jj] = mn;
;                 float rsum = 0.f;
; #pragma unroll
;                 for (int kt = 0; kt < 2; ++kt)
; #pragma unroll
;                     for (int e = 0; e < 4; ++e) { s[jj][kt][e] = __builtin_amdgcn_exp2f(s[jj][kt][e] - mn); rsum += s[jj][kt][e]; }
.LBB0_305:
	s_add_i32 s0, s65, 2
	s_cmp_ge_i32 s0, s23
	s_cselect_b64 s[60:61], -1, 0
	s_cmp_lt_i32 s0, s45
	s_cselect_b64 s[66:67], -1, 0
	s_and_b64 s[60:61], s[60:61], s[66:67]
	s_andn2_b64 vcc, exec, s[60:61]
	s_cbranch_vccnz .LBB0_300
	s_add_i32 s0, s86, s65
	s_add_i32 s0, s0, 2
	s_mul_hi_i32 s14, s0, 0x55555556
	s_lshr_b32 s15, s14, 31
	s_add_i32 s14, s14, s15
	s_mul_i32 s14, s14, 3
	s_sub_i32 s0, s0, s14
	s_lshl_b32 s0, s0, 14
	s_add_i32 s0, s0, 0
	v_add_u32_e32 v5, s50, v128
	v_add_u32_e32 v2, s0, v89
	v_add_u32_e32 v5, 0x10480, v5
	v_add_u32_e32 v3, s0, v88
	ds_read_b128 v[162:165], v5
	ds_read_b128 v[130:133], v2
	ds_read_b128 v[138:141], v3
	ds_read_b128 v[166:169], v5 offset:64
	ds_read_b128 v[134:137], v2 offset:2048
	ds_read_b128 v[142:145], v3 offset:2048
	v_add_u32_e32 v5, s50, v127
	v_add_u32_e32 v2, s0, v92
	v_add_u32_e32 v5, 0x10480, v5
	v_add_u32_e32 v3, s0, v91
	ds_read_b128 v[170:173], v5
	ds_read_b128 v[146:149], v2
	ds_read_b128 v[154:157], v3
	ds_read_b128 v[174:177], v5 offset:64
	ds_read_b128 v[150:153], v2 offset:2048
	ds_read_b128 v[158:161], v3 offset:2048
	s_waitcnt lgkmcnt(10)
	v_pk_add_f32 v[164:165], v[112:113], v[164:165]
	v_pk_add_f32 v[162:163], v[110:111], v[162:163]
	s_nop 1
	v_mfma_f32_16x16x32_bf16 v[130:133], v[130:133], v[30:33], v[162:165]
	s_nop 2
	s_waitcnt lgkmcnt(8)
	v_pk_add_f32 v[164:165], v[114:115], v[168:169]
	v_pk_add_f32 v[162:163], v[108:109], v[166:167]
	v_mfma_f32_16x16x32_bf16 v[130:133], v[138:141], v[26:29], v[130:133]
	s_waitcnt lgkmcnt(5)
	v_pk_add_f32 v[140:141], v[106:107], v[172:173]
	v_pk_add_f32 v[138:139], v[102:103], v[170:171]
	v_mfma_f32_16x16x32_bf16 v[134:137], v[134:137], v[30:33], v[162:165]
	v_mfma_f32_16x16x32_bf16 v[134:137], v[142:145], v[26:29], v[134:137]
	s_nop 2
	v_maximum3_f32 v129, v130, v131, v132
	s_waitcnt lgkmcnt(2)
	v_pk_add_f32 v[164:165], v[104:105], v[176:177]
	v_pk_add_f32 v[162:163], v[100:101], v[174:175]
	v_mfma_f32_16x16x32_bf16 v[138:141], v[146:149], v[22:25], v[138:141]
	v_mfma_f32_16x16x32_bf16 v[138:141], v[154:157], v[18:21], v[138:141]
	v_maximum3_f32 v142, v133, v134, v135
	v_maximum3_f32 v143, v136, v137, v137
	v_maximum3_f32 v129, v129, v142, v143
	v_mov_b32_e32 v142, v129
	s_nop 1
	v_permlane16_swap_b32_e32 v129, v142
	v_maximum3_f32 v129, v129, v142, v142
	v_mov_b32_e32 v142, v129
	s_nop 1
	v_permlane32_swap_b32_e32 v129, v142
	v_maximum3_f32 v129, v125, v129, v142
	s_waitcnt lgkmcnt(0)
; template <int MODE> ...
;     ...
;             s16x4 vlo[2][4], vhi[2][4];
; #pragma unroll
;             for (int jj = 0; jj < 2; ++jj)
; #pragma unroll
;                 for (int dt = 0; dt < 4; ++dt) { const LAS unsigned char* vp = Sl + vad[jj] + (32 * hf) * 128 + ((dt ^ sv) << 5);
;                     vlo[jj][dt] = __builtin_bit_cast(s16x4, __builtin_amdgcn_ds_read_tr16_b64_v4i16((LAS s16x4*)(vp)));
;                     vhi[jj][dt] = __builtin_bit_cast(s16x4, __builtin_amdgcn_ds_read_tr16_b64_v4i16((LAS s16x4*)(vp + 2048))); }
;             __builtin_amdgcn_sched_barrier(0);
;             f32x4 s[2][2];
; #pragma unroll
;             for (int jj = 0; jj < 2; ++jj)
; #pragma unroll
;                 for (int kt = 0; kt < 2; ++kt) { f32x4 a = (MODE == 0) ? bb[jj][kt] + mneg[jj][kt] : bb[jj][kt];
;                     a = __builtin_amdgcn_mfma_f32_16x16x32_bf16(kf[jj][kt][0], qf[jj][0], a, 0, 0, 0);
;                     s[jj][kt] = __builtin_amdgcn_mfma_f32_16x16x32_bf16(kf[jj][kt][1], qf[jj][1], a, 0, 0, 0); }
;             u32x4 pw[2];
; #pragma unroll
;             for (int jj = 0; jj < 2; ++jj) {
;                 const float tm = vmax3(vmax3(s[jj][0][0], s[jj][0][1], s[jj][0][2]), vmax3(s[jj][0][3], s[jj][1][0], s[jj][1][1]), vmax3(s[jj][1][2], s[jj][1][3], s[jj][1][3]));
;                 const float mn = quad_max3(mrun[jj], tm);
;                 const float alpha = __builtin_amdgcn_exp2f(mrun[jj] - mn);
;                 mrun[jj] = mn;
;                 float rsum = 0.f;
; #pragma unroll
;                 for (int kt = 0; kt < 2; ++kt)
; #pragma unroll
;                     for (int e = 0; e < 4; ++e) { s[jj][kt][e] = __builtin_amdgcn_exp2f(s[jj][kt][e] - mn); rsum += s[jj][kt][e]; }
;                 lrun[jj] = lrun[jj] * alpha + rsum;
; #pragma unroll
;                 for (int dt = 0; dt < 4; ++dt) o[jj][dt] *= alpha;
;                 pw[jj].x = cvtpk(s[jj][0][0], s[jj][0][1]); pw[jj].y = cvtpk(s[jj][0][2], s[jj][0][3]); pw[jj].z = cvtpk(s[jj][1][0], s[jj][1][1]); pw[jj].w = cvtpk(s[jj][1][2], s[jj][1][3]);
;             }
; #pragma unroll
;             for (int jj = 0; jj < 2; ++jj)
; #pragma unroll
;                 for (int dt = 0; dt < 4; ++dt) {
;                     const bf16x8 vf = (bf16x8){vlo[jj][dt][0], vlo[jj][dt][1], vlo[jj][dt][2], vlo[jj][dt][3], vhi[jj][dt][0], vhi[jj][dt][1], vhi[jj][dt][2], vhi[jj][dt][3]};
	v_mfma_f32_16x16x32_bf16 v[142:145], v[150:153], v[22:25], v[162:165]
	v_sub_f32_e32 v130, v130, v129
	v_exp_f32_e32 v146, v130
	v_sub_f32_e32 v130, v131, v129
	v_exp_f32_e32 v148, v130
	v_sub_f32_e32 v130, v132, v129
	v_mfma_f32_16x16x32_bf16 v[142:145], v[158:161], v[18:21], v[142:145]
	v_exp_f32_e32 v150, v130
	v_sub_f32_e32 v130, v133, v129
	v_exp_f32_e32 v152, v130
	v_sub_f32_e32 v130, v134, v129
	v_sub_f32_e32 v125, v125, v129
	v_exp_f32_e32 v134, v130
	v_sub_f32_e32 v130, v135, v129
	v_exp_f32_e32 v154, v130
	v_sub_f32_e32 v130, v136, v129
	v_exp_f32_e32 v136, v125
	v_sub_f32_e32 v125, v137, v129
	v_exp_f32_e32 v158, v125
	v_add_u32_e32 v2, s0, v0
	v_add_u32_e32 v3, v2, v94
	v_add_u32_e32 v4, v2, v95
	ds_read_b64_tr_b16 v[78:79], v3 offset:8192
	ds_read_b64_tr_b16 v[80:81], v3 offset:10240
	ds_read_b64_tr_b16 v[74:75], v4 offset:8192
	ds_read_b64_tr_b16 v[76:77], v4 offset:10240
	v_add_u32_e32 v3, v2, v96
	v_add_u32_e32 v2, v2, v97
	ds_read_b64_tr_b16 v[70:71], v3 offset:8192
	ds_read_b64_tr_b16 v[72:73], v3 offset:10240
	ds_read_b64_tr_b16 v[66:67], v2 offset:8192
	ds_read_b64_tr_b16 v[68:69], v2 offset:10240
	v_add_u32_e32 v2, s0, v126
	v_add_u32_e32 v3, v2, v94
	v_add_u32_e32 v4, v2, v95
	ds_read_b64_tr_b16 v[14:15], v3 offset:8192
	ds_read_b64_tr_b16 v[16:17], v3 offset:10240
	ds_read_b64_tr_b16 v[10:11], v4 offset:8192
	ds_read_b64_tr_b16 v[12:13], v4 offset:10240
	v_add_u32_e32 v3, v2, v96
	v_add_u32_e32 v4, v2, v97
	ds_read_b64_tr_b16 v[6:7], v3 offset:8192
	ds_read_b64_tr_b16 v[8:9], v3 offset:10240
	ds_read_b64_tr_b16 v[2:3], v4 offset:8192
	ds_read_b64_tr_b16 v[4:5], v4 offset:10240
	v_maximum3_f32 v125, v138, v139, v140
	v_maximum3_f32 v133, v141, v142, v143
	v_maximum3_f32 v135, v144, v145, v145
	v_maximum3_f32 v125, v125, v133, v135
	v_mov_b32_e32 v133, v125
	s_nop 1
	v_permlane16_swap_b32_e32 v125, v133
	v_maximum3_f32 v125, v125, v133, v133
	v_mov_b32_e32 v133, v125
	s_nop 1
	v_permlane32_swap_b32_e32 v125, v133
	v_maximum3_f32 v160, v124, v125, v133
	v_sub_f32_e32 v125, v138, v160
	v_sub_f32_e32 v135, v140, v160
	v_sub_f32_e32 v138, v143, v160
	v_exp_f32_e32 v156, v130
	v_pk_mul_f32 v[56:57], v[56:57], v[136:137] op_sel_hi:[1,0]
	v_pk_mul_f32 v[54:55], v[54:55], v[136:137] op_sel_hi:[1,0]
	v_pk_mul_f32 v[64:65], v[64:65], v[136:137] op_sel_hi:[1,0]
	v_pk_mul_f32 v[62:63], v[62:63], v[136:137] op_sel_hi:[1,0]
	v_pk_mul_f32 v[60:61], v[60:61], v[136:137] op_sel_hi:[1,0]
	v_pk_mul_f32 v[58:59], v[58:59], v[136:137] op_sel_hi:[1,0]
	v_pk_mul_f32 v[52:53], v[52:53], v[136:137] op_sel_hi:[1,0]
	v_pk_mul_f32 v[50:51], v[50:51], v[136:137] op_sel_hi:[1,0]
	v_sub_f32_e32 v137, v124, v160
	v_exp_f32_e32 v151, v135
	v_sub_f32_e32 v135, v141, v160
	v_exp_f32_e32 v155, v138
	v_sub_f32_e32 v138, v144, v160
	v_exp_f32_e32 v147, v125
	v_sub_f32_e32 v125, v139, v160
	v_exp_f32_e32 v153, v135
	v_sub_f32_e32 v135, v142, v160
	v_exp_f32_e32 v157, v138
	v_sub_f32_e32 v138, v145, v160
	v_exp_f32_e32 v137, v137
	v_exp_f32_e32 v149, v125
	v_exp_f32_e32 v135, v135
	v_exp_f32_e32 v159, v138
	v_cvt_pk_bf16_f32 v130, v146, v148
	v_cvt_pk_bf16_f32 v131, v150, v152
	v_cvt_pk_bf16_f32 v132, v134, v154
	v_cvt_pk_bf16_f32 v133, v156, v158
	v_pk_add_f32 v[124:125], v[146:147], 0 op_sel_hi:[1,0]
	s_waitcnt lgkmcnt(12)
	v_mfma_f32_16x16x32_bf16 v[62:65], v[74:77], v[130:133], v[62:65]
	v_mov_b32_e32 v76, v137
	v_pk_add_f32 v[124:125], v[148:149], v[124:125]
	v_pk_mul_f32 v[48:49], v[48:49], v[76:77] op_sel_hi:[1,0]
	s_waitcnt lgkmcnt(10)
	v_mfma_f32_16x16x32_bf16 v[58:61], v[70:73], v[130:133], v[58:61]
	v_pk_mul_f32 v[46:47], v[46:47], v[76:77] op_sel_hi:[1,0]
	v_cvt_pk_bf16_f32 v70, v147, v149
	v_cvt_pk_bf16_f32 v71, v151, v153
	v_cvt_pk_bf16_f32 v72, v135, v155
	v_cvt_pk_bf16_f32 v73, v157, v159
	v_mfma_f32_16x16x32_bf16 v[54:57], v[78:81], v[130:133], v[54:57]
	v_pk_add_f32 v[78:79], v[150:151], v[124:125]
	v_pk_add_f32 v[78:79], v[152:153], v[78:79]
	s_waitcnt lgkmcnt(6)
	v_mfma_f32_16x16x32_bf16 v[46:49], v[14:17], v[70:73], v[46:49]
	v_pk_mul_f32 v[16:17], v[44:45], v[76:77] op_sel_hi:[1,0]
	v_pk_mul_f32 v[14:15], v[42:43], v[76:77] op_sel_hi:[1,0]
	v_pk_add_f32 v[74:75], v[134:135], v[78:79]
	v_mfma_f32_16x16x32_bf16 v[50:53], v[66:69], v[130:133], v[50:53]
	v_pk_add_f32 v[74:75], v[154:155], v[74:75]
	v_pk_add_f32 v[66:67], v[156:157], v[74:75]
	s_waitcnt lgkmcnt(4)
	v_mfma_f32_16x16x32_bf16 v[42:45], v[10:13], v[70:73], v[14:17]
	v_pk_mul_f32 v[12:13], v[40:41], v[76:77] op_sel_hi:[1,0]
	v_pk_mul_f32 v[10:11], v[38:39], v[76:77] op_sel_hi:[1,0]
	v_pk_add_f32 v[14:15], v[158:159], v[66:67]
	s_waitcnt lgkmcnt(2)
	v_mfma_f32_16x16x32_bf16 v[38:41], v[6:9], v[70:73], v[10:13]
	v_pk_mul_f32 v[8:9], v[36:37], v[76:77] op_sel_hi:[1,0]
	v_pk_mul_f32 v[6:7], v[34:35], v[76:77] op_sel_hi:[1,0]
	v_pk_fma_f32 v[98:99], v[98:99], v[136:137], v[14:15]
	s_waitcnt lgkmcnt(0)
	v_mfma_f32_16x16x32_bf16 v[34:37], v[2:5], v[70:73], v[6:9]
	v_mov_b32_e32 v125, v129
	v_mov_b32_e32 v124, v160
	s_branch .LBB0_300
